# all GEMM K-loops (incl. out_proj and split-K loops): drop per-phase s_setprio flips and duplicate lgkmcnt(0)
# speedup vs baseline: 1.0073x; 1.0021x over previous
.LBB0_940:
	s_add_u32 s36, s30, s34
	v_add_u32_e32 v3, s51, v181
	s_addc_u32 s37, s31, s35
	ds_read_b128 v[138:141], v3
	ds_read_b128 v[142:145], v3 offset:1024
	ds_read_b128 v[146:149], v3 offset:2048
	ds_read_b128 v[150:153], v3 offset:3072
	s_add_u32 s36, s36, 0x100
	s_addc_u32 s37, s37, 0
	s_add_u32 s67, s64, s34
	s_addc_u32 s68, s65, s35
	s_cmpk_eq_i32 s34, 0xf00
	s_cselect_b32 s38, s62, s36
	s_cselect_b32 s36, s63, s67
	s_cselect_b32 s39, s23, s37
	s_cselect_b32 s37, s21, s68
	v_lshl_add_u64 v[4:5], v[134:135], 0, s[34:35]
	s_add_i32 m0, s29, 0xc000
	ds_read_b128 v[154:157], v194
	ds_read_b128 v[158:161], v194 offset:1024
	ds_read_b128 v[162:165], v194 offset:2048
	ds_read_b128 v[166:169], v194 offset:3072
	ds_read_b128 v[196:199], v194 offset:4096
	ds_read_b128 v[200:203], v194 offset:5120
	ds_read_b128 v[206:209], v194 offset:6144
	ds_read_b128 v[212:215], v194 offset:7168
	global_load_lds_dwordx4 v[4:5], off
	v_lshl_add_u64 v[4:5], v[136:137], 0, s[34:35]
	s_add_i32 m0, s29, 0xe000
	s_nop 0
	global_load_lds_dwordx4 v[4:5], off
	s_waitcnt lgkmcnt(8)
	s_barrier
	s_waitcnt lgkmcnt(0)
	v_mfma_f32_16x16x32_bf16 v[130:133], v[138:141], v[154:157], v[130:133]
	v_mfma_f32_16x16x32_bf16 v[126:129], v[146:149], v[154:157], v[126:129]
	v_mfma_f32_16x16x32_bf16 v[114:117], v[138:141], v[162:165], v[114:117]
	v_mfma_f32_16x16x32_bf16 v[110:113], v[146:149], v[162:165], v[110:113]
	v_mfma_f32_16x16x32_bf16 v[98:101], v[138:141], v[196:199], v[98:101]
	v_mfma_f32_16x16x32_bf16 v[94:97], v[146:149], v[196:199], v[94:97]
	v_mfma_f32_16x16x32_bf16 v[82:85], v[138:141], v[206:209], v[82:85]
	v_mfma_f32_16x16x32_bf16 v[78:81], v[146:149], v[206:209], v[78:81]
	v_mfma_f32_16x16x32_bf16 v[130:133], v[142:145], v[158:161], v[130:133]
	v_mfma_f32_16x16x32_bf16 v[126:129], v[150:153], v[158:161], v[126:129]
	v_mfma_f32_16x16x32_bf16 v[114:117], v[142:145], v[166:169], v[114:117]
	v_mfma_f32_16x16x32_bf16 v[110:113], v[150:153], v[166:169], v[110:113]
	v_mfma_f32_16x16x32_bf16 v[98:101], v[142:145], v[200:203], v[98:101]
	v_mfma_f32_16x16x32_bf16 v[94:97], v[150:153], v[200:203], v[94:97]
	v_mfma_f32_16x16x32_bf16 v[82:85], v[142:145], v[212:215], v[82:85]
	v_mfma_f32_16x16x32_bf16 v[78:81], v[150:153], v[212:215], v[78:81]
	s_barrier
	s_add_i32 s67, s51, s43
	v_add_u32_e32 v3, s52, v181
	v_lshl_add_u64 v[192:193], s[36:37], 0, v[174:175]
	s_mov_b32 m0, s67
	ds_read_b128 v[216:219], v3
	ds_read_b128 v[220:223], v3 offset:1024
	ds_read_b128 v[224:227], v3 offset:2048
	ds_read_b128 v[228:231], v3 offset:3072
	global_load_lds_dwordx4 v[192:193], off
	v_lshl_add_u64 v[232:233], s[36:37], 0, v[176:177]
	s_add_i32 m0, s67, 0x2000
	s_nop 0
	global_load_lds_dwordx4 v[232:233], off
	s_barrier
	s_waitcnt lgkmcnt(0)
	v_mfma_f32_16x16x32_bf16 v[122:125], v[216:219], v[154:157], v[122:125]
	v_mfma_f32_16x16x32_bf16 v[118:121], v[224:227], v[154:157], v[118:121]
	v_mfma_f32_16x16x32_bf16 v[106:109], v[216:219], v[162:165], v[106:109]
	v_mfma_f32_16x16x32_bf16 v[102:105], v[224:227], v[162:165], v[102:105]
	v_mfma_f32_16x16x32_bf16 v[90:93], v[216:219], v[196:199], v[90:93]
	v_mfma_f32_16x16x32_bf16 v[86:89], v[224:227], v[196:199], v[86:89]
	v_mfma_f32_16x16x32_bf16 v[74:77], v[216:219], v[206:209], v[74:77]
	v_mfma_f32_16x16x32_bf16 v[70:73], v[224:227], v[206:209], v[70:73]
	v_mfma_f32_16x16x32_bf16 v[122:125], v[220:223], v[158:161], v[122:125]
	v_mfma_f32_16x16x32_bf16 v[118:121], v[228:231], v[158:161], v[118:121]
	v_mfma_f32_16x16x32_bf16 v[106:109], v[220:223], v[166:169], v[106:109]
	v_mfma_f32_16x16x32_bf16 v[102:105], v[228:231], v[166:169], v[102:105]
	v_mfma_f32_16x16x32_bf16 v[90:93], v[220:223], v[200:203], v[90:93]
	v_mfma_f32_16x16x32_bf16 v[86:89], v[228:231], v[200:203], v[86:89]
	v_mfma_f32_16x16x32_bf16 v[74:77], v[220:223], v[212:215], v[74:77]
	v_mfma_f32_16x16x32_bf16 v[70:73], v[228:231], v[212:215], v[70:73]
	s_mov_b32 m0, s29
	v_lshl_add_u64 v[234:235], s[38:39], 0, v[170:171]
	s_barrier
	ds_read_b128 v[154:157], v194 offset:16384
	ds_read_b128 v[158:161], v194 offset:17408
	ds_read_b128 v[162:165], v194 offset:18432
	ds_read_b128 v[166:169], v194 offset:19456
	ds_read_b128 v[196:199], v194 offset:20480
	ds_read_b128 v[200:203], v194 offset:21504
	ds_read_b128 v[206:209], v194 offset:22528
	ds_read_b128 v[212:215], v194 offset:23552
	global_load_lds_dwordx4 v[234:235], off
	v_lshl_add_u64 v[236:237], s[38:39], 0, v[172:173]
	s_mov_b32 m0, s44
	s_nop 0
	global_load_lds_dwordx4 v[236:237], off
	s_barrier
	s_waitcnt lgkmcnt(0)
	v_mfma_f32_16x16x32_bf16 v[66:69], v[138:141], v[154:157], v[66:69]
	v_mfma_f32_16x16x32_bf16 v[62:65], v[146:149], v[154:157], v[62:65]
	v_mfma_f32_16x16x32_bf16 v[50:53], v[138:141], v[162:165], v[50:53]
	v_mfma_f32_16x16x32_bf16 v[46:49], v[146:149], v[162:165], v[46:49]
	v_mfma_f32_16x16x32_bf16 v[34:37], v[138:141], v[196:199], v[34:37]
	v_mfma_f32_16x16x32_bf16 v[30:33], v[146:149], v[196:199], v[30:33]
	v_mfma_f32_16x16x32_bf16 v[18:21], v[138:141], v[206:209], v[18:21]
	v_mfma_f32_16x16x32_bf16 v[14:17], v[146:149], v[206:209], v[14:17]
	v_mfma_f32_16x16x32_bf16 v[66:69], v[142:145], v[158:161], v[66:69]
	v_mfma_f32_16x16x32_bf16 v[62:65], v[150:153], v[158:161], v[62:65]
	v_mfma_f32_16x16x32_bf16 v[50:53], v[142:145], v[166:169], v[50:53]
	v_mfma_f32_16x16x32_bf16 v[46:49], v[150:153], v[166:169], v[46:49]
	v_mfma_f32_16x16x32_bf16 v[34:37], v[142:145], v[200:203], v[34:37]
	v_mfma_f32_16x16x32_bf16 v[30:33], v[150:153], v[200:203], v[30:33]
	v_mfma_f32_16x16x32_bf16 v[18:21], v[142:145], v[212:215], v[18:21]
	v_mfma_f32_16x16x32_bf16 v[14:17], v[150:153], v[212:215], v[14:17]
	s_barrier
	s_add_u32 s68, s36, 0x80000
	s_addc_u32 s69, s37, 0
	s_add_i32 s67, s52, s43
	v_lshl_add_u64 v[4:5], s[68:69], 0, v[174:175]
	s_mov_b32 m0, s67
	s_nop 0
	global_load_lds_dwordx4 v[4:5], off
	v_lshl_add_u64 v[4:5], s[68:69], 0, v[176:177]
	s_add_i32 m0, s67, 0x2000
	s_nop 0
	global_load_lds_dwordx4 v[4:5], off
	s_waitcnt vmcnt(6)
	s_barrier
	v_mfma_f32_16x16x32_bf16 v[58:61], v[216:219], v[154:157], v[58:61]
	v_mfma_f32_16x16x32_bf16 v[54:57], v[224:227], v[154:157], v[54:57]
	v_mfma_f32_16x16x32_bf16 v[42:45], v[216:219], v[162:165], v[42:45]
	v_mfma_f32_16x16x32_bf16 v[38:41], v[224:227], v[162:165], v[38:41]
	v_mfma_f32_16x16x32_bf16 v[26:29], v[216:219], v[196:199], v[26:29]
	v_mfma_f32_16x16x32_bf16 v[22:25], v[224:227], v[196:199], v[22:25]
	v_mfma_f32_16x16x32_bf16 v[10:13], v[216:219], v[206:209], v[10:13]
	v_mfma_f32_16x16x32_bf16 v[4:7], v[224:227], v[206:209], v[6:9]
	v_mfma_f32_16x16x32_bf16 v[58:61], v[220:223], v[158:161], v[58:61]
	v_mfma_f32_16x16x32_bf16 v[54:57], v[228:231], v[158:161], v[54:57]
	v_mfma_f32_16x16x32_bf16 v[42:45], v[220:223], v[166:169], v[42:45]
	v_mfma_f32_16x16x32_bf16 v[38:41], v[228:231], v[166:169], v[38:41]
	v_mfma_f32_16x16x32_bf16 v[26:29], v[220:223], v[200:203], v[26:29]
	v_mfma_f32_16x16x32_bf16 v[22:25], v[228:231], v[200:203], v[22:25]
	v_mfma_f32_16x16x32_bf16 v[10:13], v[220:223], v[212:215], v[10:13]
	v_mfma_f32_16x16x32_bf16 v[4:7], v[228:231], v[212:215], v[4:7]
	s_add_i32 s67, 0, 0x18000
	v_add_u32_e32 v3, s67, v181
	s_barrier
	ds_read_b128 v[138:141], v3
	ds_read_b128 v[142:145], v3 offset:1024
	ds_read_b128 v[146:149], v3 offset:2048
	ds_read_b128 v[150:153], v3 offset:3072
	s_add_u32 s38, s38, 0x80000
	s_addc_u32 s39, s39, 0
	s_mov_b32 m0, s45
	v_lshl_add_u64 v[8:9], s[38:39], 0, v[170:171]
	ds_read_b128 v[154:157], v194 offset:32768
	ds_read_b128 v[158:161], v194 offset:33792
	ds_read_b128 v[162:165], v194 offset:34816
	ds_read_b128 v[166:169], v194 offset:35840
	ds_read_b128 v[196:199], v194 offset:36864
	ds_read_b128 v[200:203], v194 offset:37888
	ds_read_b128 v[206:209], v194 offset:38912
	ds_read_b128 v[212:215], v194 offset:39936
	global_load_lds_dwordx4 v[8:9], off
	v_lshl_add_u64 v[8:9], s[38:39], 0, v[172:173]
	s_mov_b32 m0, s46
	s_nop 0
	global_load_lds_dwordx4 v[8:9], off
	s_waitcnt lgkmcnt(8)
	s_barrier
	s_waitcnt lgkmcnt(0)
	v_mfma_f32_16x16x32_bf16 v[130:133], v[138:141], v[154:157], v[130:133]
	v_mfma_f32_16x16x32_bf16 v[126:129], v[146:149], v[154:157], v[126:129]
	v_mfma_f32_16x16x32_bf16 v[114:117], v[138:141], v[162:165], v[114:117]
	v_mfma_f32_16x16x32_bf16 v[110:113], v[146:149], v[162:165], v[110:113]
	v_mfma_f32_16x16x32_bf16 v[98:101], v[138:141], v[196:199], v[98:101]
	v_mfma_f32_16x16x32_bf16 v[94:97], v[146:149], v[196:199], v[94:97]
	v_mfma_f32_16x16x32_bf16 v[82:85], v[138:141], v[206:209], v[82:85]
	v_mfma_f32_16x16x32_bf16 v[78:81], v[146:149], v[206:209], v[78:81]
	v_mfma_f32_16x16x32_bf16 v[130:133], v[142:145], v[158:161], v[130:133]
	v_mfma_f32_16x16x32_bf16 v[126:129], v[150:153], v[158:161], v[126:129]
	v_mfma_f32_16x16x32_bf16 v[114:117], v[142:145], v[166:169], v[114:117]
	v_mfma_f32_16x16x32_bf16 v[110:113], v[150:153], v[166:169], v[110:113]
	v_mfma_f32_16x16x32_bf16 v[98:101], v[142:145], v[200:203], v[98:101]
	v_mfma_f32_16x16x32_bf16 v[94:97], v[150:153], v[200:203], v[94:97]
	v_mfma_f32_16x16x32_bf16 v[82:85], v[142:145], v[212:215], v[82:85]
	v_mfma_f32_16x16x32_bf16 v[78:81], v[150:153], v[212:215], v[78:81]
	s_barrier
	s_add_i32 s38, 0, 0x1c000
	s_add_i32 s39, s67, s43
	v_add_u32_e32 v3, s38, v181
	v_lshl_add_u64 v[8:9], v[192:193], 0, s[10:11]
	s_mov_b32 m0, s39
	ds_read_b128 v[216:219], v3
	ds_read_b128 v[220:223], v3 offset:1024
	ds_read_b128 v[224:227], v3 offset:2048
	ds_read_b128 v[228:231], v3 offset:3072
	global_load_lds_dwordx4 v[8:9], off
	v_lshl_add_u64 v[8:9], v[232:233], 0, s[10:11]
	s_add_i32 m0, s39, 0x2000
	s_nop 0
	global_load_lds_dwordx4 v[8:9], off
	s_barrier
	s_waitcnt lgkmcnt(0)
	v_mfma_f32_16x16x32_bf16 v[122:125], v[216:219], v[154:157], v[122:125]
	v_mfma_f32_16x16x32_bf16 v[118:121], v[224:227], v[154:157], v[118:121]
	v_mfma_f32_16x16x32_bf16 v[106:109], v[216:219], v[162:165], v[106:109]
	v_mfma_f32_16x16x32_bf16 v[102:105], v[224:227], v[162:165], v[102:105]
	v_mfma_f32_16x16x32_bf16 v[90:93], v[216:219], v[196:199], v[90:93]
	v_mfma_f32_16x16x32_bf16 v[86:89], v[224:227], v[196:199], v[86:89]
	v_mfma_f32_16x16x32_bf16 v[74:77], v[216:219], v[206:209], v[74:77]
	v_mfma_f32_16x16x32_bf16 v[70:73], v[224:227], v[206:209], v[70:73]
	v_mfma_f32_16x16x32_bf16 v[122:125], v[220:223], v[158:161], v[122:125]
	v_mfma_f32_16x16x32_bf16 v[118:121], v[228:231], v[158:161], v[118:121]
	v_mfma_f32_16x16x32_bf16 v[106:109], v[220:223], v[166:169], v[106:109]
	v_mfma_f32_16x16x32_bf16 v[102:105], v[228:231], v[166:169], v[102:105]
	v_mfma_f32_16x16x32_bf16 v[90:93], v[220:223], v[200:203], v[90:93]
	v_mfma_f32_16x16x32_bf16 v[86:89], v[228:231], v[200:203], v[86:89]
	v_mfma_f32_16x16x32_bf16 v[74:77], v[220:223], v[212:215], v[74:77]
	v_mfma_f32_16x16x32_bf16 v[70:73], v[228:231], v[212:215], v[70:73]
	s_mov_b32 m0, s49
	v_lshl_add_u64 v[8:9], v[234:235], 0, s[10:11]
	s_barrier
	ds_read_b128 v[154:157], v194 offset:49152
	ds_read_b128 v[158:161], v194 offset:50176
	ds_read_b128 v[162:165], v194 offset:51200
	ds_read_b128 v[166:169], v194 offset:52224
	ds_read_b128 v[196:199], v194 offset:53248
	ds_read_b128 v[200:203], v194 offset:54272
	ds_read_b128 v[206:209], v194 offset:55296
	ds_read_b128 v[212:215], v194 offset:56320
	global_load_lds_dwordx4 v[8:9], off
	v_lshl_add_u64 v[8:9], v[236:237], 0, s[10:11]
	s_mov_b32 m0, s50
	s_nop 0
	global_load_lds_dwordx4 v[8:9], off
	s_barrier
	s_waitcnt lgkmcnt(0)
	v_mfma_f32_16x16x32_bf16 v[66:69], v[138:141], v[154:157], v[66:69]
	v_mfma_f32_16x16x32_bf16 v[62:65], v[146:149], v[154:157], v[62:65]
	v_mfma_f32_16x16x32_bf16 v[50:53], v[138:141], v[162:165], v[50:53]
	v_mfma_f32_16x16x32_bf16 v[46:49], v[146:149], v[162:165], v[46:49]
	v_mfma_f32_16x16x32_bf16 v[34:37], v[138:141], v[196:199], v[34:37]
	v_mfma_f32_16x16x32_bf16 v[30:33], v[146:149], v[196:199], v[30:33]
	v_mfma_f32_16x16x32_bf16 v[18:21], v[138:141], v[206:209], v[18:21]
	v_mfma_f32_16x16x32_bf16 v[14:17], v[146:149], v[206:209], v[14:17]
	v_mfma_f32_16x16x32_bf16 v[66:69], v[142:145], v[158:161], v[66:69]
	v_mfma_f32_16x16x32_bf16 v[62:65], v[150:153], v[158:161], v[62:65]
	v_mfma_f32_16x16x32_bf16 v[50:53], v[142:145], v[166:169], v[50:53]
	v_mfma_f32_16x16x32_bf16 v[46:49], v[150:153], v[166:169], v[46:49]
	v_mfma_f32_16x16x32_bf16 v[34:37], v[142:145], v[200:203], v[34:37]
	v_mfma_f32_16x16x32_bf16 v[30:33], v[150:153], v[200:203], v[30:33]
	v_mfma_f32_16x16x32_bf16 v[18:21], v[142:145], v[212:215], v[18:21]
	v_mfma_f32_16x16x32_bf16 v[14:17], v[150:153], v[212:215], v[14:17]
	s_barrier
	s_add_u32 s36, s36, 0x80080
	s_addc_u32 s37, s37, 0
	s_add_i32 s38, s38, s43
	v_lshl_add_u64 v[8:9], s[36:37], 0, v[174:175]
	s_mov_b32 m0, s38
	s_nop 0
	global_load_lds_dwordx4 v[8:9], off
	v_lshl_add_u64 v[8:9], s[36:37], 0, v[176:177]
	s_add_i32 m0, s38, 0x2000
	s_nop 0
	global_load_lds_dwordx4 v[8:9], off
	s_waitcnt vmcnt(6)
	s_barrier
	v_mfma_f32_16x16x32_bf16 v[58:61], v[216:219], v[154:157], v[58:61]
	v_mfma_f32_16x16x32_bf16 v[54:57], v[224:227], v[154:157], v[54:57]
	v_mfma_f32_16x16x32_bf16 v[42:45], v[216:219], v[162:165], v[42:45]
	v_mfma_f32_16x16x32_bf16 v[38:41], v[224:227], v[162:165], v[38:41]
	v_mfma_f32_16x16x32_bf16 v[26:29], v[216:219], v[196:199], v[26:29]
	v_mfma_f32_16x16x32_bf16 v[22:25], v[224:227], v[196:199], v[22:25]
	v_mfma_f32_16x16x32_bf16 v[8:11], v[216:219], v[206:209], v[10:13]
	v_mfma_f32_16x16x32_bf16 v[4:7], v[224:227], v[206:209], v[4:7]
	v_mfma_f32_16x16x32_bf16 v[58:61], v[220:223], v[158:161], v[58:61]
	v_mfma_f32_16x16x32_bf16 v[54:57], v[228:231], v[158:161], v[54:57]
	v_mfma_f32_16x16x32_bf16 v[42:45], v[220:223], v[166:169], v[42:45]
	v_mfma_f32_16x16x32_bf16 v[38:41], v[228:231], v[166:169], v[38:41]
	v_mfma_f32_16x16x32_bf16 v[26:29], v[220:223], v[200:203], v[26:29]
	v_mfma_f32_16x16x32_bf16 v[22:25], v[228:231], v[200:203], v[22:25]
	v_mfma_f32_16x16x32_bf16 v[10:13], v[220:223], v[212:215], v[8:11]
	v_mfma_f32_16x16x32_bf16 v[6:9], v[228:231], v[212:215], v[4:7]
	s_add_i32 s36, s66, 2
	s_add_u32 s34, s34, 0x100
	s_addc_u32 s35, s35, 0
	s_cmp_gt_u32 s66, 29
	s_barrier
	s_cbranch_scc1 .LBB0_927
	s_mov_b32 s66, s36
	s_cmp_lt_i32 s66, 16
	s_cbranch_scc1 .LBB0_936
	s_branch .LBB0_935

.LBB0_948:
	s_add_i32 s24, 0, 0x18000
	s_lshl_b32 s8, s8, 5
	s_add_i32 s16, s24, s19
	s_mov_b64 s[12:13], 0x80
	s_lshl_b32 s21, s20, 13
	s_and_b32 s8, s8, 0x60
	v_lshl_add_u64 v[18:19], v[34:35], 0, s[12:13]
	s_mov_b32 m0, s16
	s_add_i32 s17, s16, 0x2000
	s_add_i32 s10, s9, 0x8000
	s_add_i32 s11, s9, 0xa000
	s_waitcnt vmcnt(4)
	s_barrier
	global_load_lds_dwordx4 v[18:19], off
	v_lshl_add_u64 v[20:21], v[36:37], 0, s[12:13]
	s_mov_b32 m0, s17
	s_add_u32 s22, s4, 0x80080
	global_load_lds_dwordx4 v[20:21], off
	v_lshl_add_u64 v[2:3], v[32:33], 0, s[12:13]
	s_mov_b32 m0, s10
	s_addc_u32 s23, s5, 0
	s_add_i32 s25, 0, 0x1c000
	global_load_lds_dwordx4 v[2:3], off
	v_lshl_add_u64 v[6:7], v[30:31], 0, s[12:13]
	s_mov_b32 m0, s11
	s_add_i32 s12, s25, s19
	global_load_lds_dwordx4 v[6:7], off
	v_lshl_add_u64 v[10:11], s[22:23], 0, v[170:171]
	s_mov_b32 m0, s12
	s_add_i32 s13, s12, 0x2000
	global_load_lds_dwordx4 v[10:11], off
	v_lshl_add_u64 v[12:13], s[22:23], 0, v[172:173]
	s_mov_b32 m0, s13
	v_lshl_or_b32 v1, s8, 7, v1
	global_load_lds_dwordx4 v[12:13], off
	s_add_i32 s22, 0, 0x10000
	v_add_u32_e32 v152, s22, v1
	s_waitcnt vmcnt(6)
	s_barrier
	ds_read_b128 v[38:41], v152
	ds_read_b128 v[42:45], v152 offset:1024
	ds_read_b128 v[46:49], v152 offset:2048
	ds_read_b128 v[50:53], v152 offset:3072
	v_lshlrev_b32_e32 v5, 2, v178
	v_lshl_or_b32 v4, v178, 6, v204
	v_and_b32_e32 v5, 32, v5
	v_lshl_or_b32 v14, s20, 6, v178
	v_bitop3_b32 v4, v4, s21, v5 bitop3:0xde
	v_mov_b32_e32 v15, v171
	v_add_u32_e32 v153, 0, v4
	s_add_i32 s26, 0, 0x14000
	v_lshlrev_b64 v[8:9], 12, v[14:15]
	v_or_b32_e32 v4, 16, v14
	v_mov_b32_e32 v5, v171
	v_or_b32_e32 v16, 32, v14
	v_mov_b32_e32 v17, v171
	v_or_b32_e32 v14, 48, v14
	v_add_u32_e32 v154, s26, v1
	v_add_u32_e32 v155, s24, v1
	v_add_u32_e32 v1, s25, v1
	v_lshlrev_b64 v[4:5], 12, v[4:5]
	v_lshlrev_b64 v[16:17], 12, v[16:17]
	v_lshlrev_b64 v[14:15], 12, v[14:15]
	s_add_u32 s20, s0, 0x80080
	s_addc_u32 s21, s1, 0
	s_add_i32 s23, s9, 0xc000
	v_lshl_add_u64 v[86:87], s[20:21], 0, v[170:171]
	s_mov_b32 m0, s23
	ds_read_b128 v[54:57], v153
	ds_read_b128 v[58:61], v153 offset:1024
	ds_read_b128 v[62:65], v153 offset:2048
	ds_read_b128 v[66:69], v153 offset:3072
	ds_read_b128 v[70:73], v153 offset:4096
	ds_read_b128 v[74:77], v153 offset:5120
	ds_read_b128 v[78:81], v153 offset:6144
	ds_read_b128 v[82:85], v153 offset:7168
	global_load_lds_dwordx4 v[86:87], off
	v_lshl_add_u64 v[86:87], s[20:21], 0, v[172:173]
	s_add_i32 s20, s9, 0xe000
	s_mov_b32 m0, s20
	s_nop 0
	global_load_lds_dwordx4 v[86:87], off
	s_waitcnt lgkmcnt(8)
	s_barrier
	s_waitcnt lgkmcnt(0)
	v_mfma_f32_16x16x32_bf16 v[86:89], v[38:41], v[54:57], 0
	v_mfma_f32_16x16x32_bf16 v[94:97], v[38:41], v[62:65], 0
	v_mfma_f32_16x16x32_bf16 v[102:105], v[38:41], v[70:73], 0
	v_mfma_f32_16x16x32_bf16 v[38:41], v[38:41], v[78:81], 0
	v_mfma_f32_16x16x32_bf16 v[86:89], v[42:45], v[58:61], v[86:89]
	v_mfma_f32_16x16x32_bf16 v[90:93], v[46:49], v[54:57], 0
	v_mfma_f32_16x16x32_bf16 v[94:97], v[42:45], v[66:69], v[94:97]
	v_mfma_f32_16x16x32_bf16 v[98:101], v[46:49], v[62:65], 0
	v_mfma_f32_16x16x32_bf16 v[102:105], v[42:45], v[74:77], v[102:105]
	v_mfma_f32_16x16x32_bf16 v[106:109], v[46:49], v[70:73], 0
	v_mfma_f32_16x16x32_bf16 v[38:41], v[42:45], v[82:85], v[38:41]
	v_mfma_f32_16x16x32_bf16 v[42:45], v[46:49], v[78:81], 0
	v_mfma_f32_16x16x32_bf16 v[90:93], v[50:53], v[58:61], v[90:93]
	v_mfma_f32_16x16x32_bf16 v[98:101], v[50:53], v[66:69], v[98:101]
	v_mfma_f32_16x16x32_bf16 v[106:109], v[50:53], v[74:77], v[106:109]
	v_mfma_f32_16x16x32_bf16 v[42:45], v[50:53], v[82:85], v[42:45]
	s_barrier
	s_mov_b64 s[24:25], 0x100
	s_add_i32 s21, s22, s19
	v_lshl_add_u64 v[118:119], v[34:35], 0, s[24:25]
	s_mov_b32 m0, s21
	s_add_i32 s22, s21, 0x2000
	ds_read_b128 v[46:49], v154
	ds_read_b128 v[50:53], v154 offset:1024
	ds_read_b128 v[110:113], v154 offset:2048
	ds_read_b128 v[114:117], v154 offset:3072
	global_load_lds_dwordx4 v[118:119], off
	v_lshl_add_u64 v[118:119], v[36:37], 0, s[24:25]
	s_mov_b32 m0, s22
	s_nop 0
	global_load_lds_dwordx4 v[118:119], off
	s_barrier
	s_waitcnt lgkmcnt(0)
	v_mfma_f32_16x16x32_bf16 v[118:121], v[46:49], v[54:57], 0
	v_mfma_f32_16x16x32_bf16 v[54:57], v[110:113], v[54:57], 0
	v_mfma_f32_16x16x32_bf16 v[118:121], v[50:53], v[58:61], v[118:121]
	v_mfma_f32_16x16x32_bf16 v[54:57], v[114:117], v[58:61], v[54:57]
	v_mfma_f32_16x16x32_bf16 v[58:61], v[46:49], v[62:65], 0
	v_mfma_f32_16x16x32_bf16 v[62:65], v[110:113], v[62:65], 0
	v_mfma_f32_16x16x32_bf16 v[58:61], v[50:53], v[66:69], v[58:61]
	v_mfma_f32_16x16x32_bf16 v[62:65], v[114:117], v[66:69], v[62:65]
	v_mfma_f32_16x16x32_bf16 v[66:69], v[46:49], v[70:73], 0
	v_mfma_f32_16x16x32_bf16 v[46:49], v[46:49], v[78:81], 0
	v_mfma_f32_16x16x32_bf16 v[66:69], v[50:53], v[74:77], v[66:69]
	v_mfma_f32_16x16x32_bf16 v[70:73], v[110:113], v[70:73], 0
	v_mfma_f32_16x16x32_bf16 v[46:49], v[50:53], v[82:85], v[46:49]
	v_mfma_f32_16x16x32_bf16 v[50:53], v[110:113], v[78:81], 0
	v_mfma_f32_16x16x32_bf16 v[70:73], v[114:117], v[74:77], v[70:73]
	v_mfma_f32_16x16x32_bf16 v[50:53], v[114:117], v[82:85], v[50:53]
	s_mov_b32 m0, s9
	v_lshl_add_u64 v[74:75], v[32:33], 0, s[24:25]
	s_barrier
	global_load_lds_dwordx4 v[74:75], off
	v_lshl_add_u64 v[74:75], v[30:31], 0, s[24:25]
	s_mov_b32 m0, s18
	s_nop 0
	global_load_lds_dwordx4 v[74:75], off
	s_barrier
	s_waitcnt lgkmcnt(0)
	s_barrier
	s_add_u32 s24, s4, 0x80100
	s_addc_u32 s25, s5, 0
	s_add_i32 s19, s26, s19
	v_lshl_add_u64 v[74:75], s[24:25], 0, v[170:171]
	s_mov_b32 m0, s19
	s_nop 0
	global_load_lds_dwordx4 v[74:75], off
	v_lshl_add_u64 v[74:75], s[24:25], 0, v[172:173]
	s_add_i32 s24, s19, 0x2000
	s_mov_b32 m0, s24
	s_nop 0
	global_load_lds_dwordx4 v[74:75], off
	s_waitcnt vmcnt(6)
	s_barrier
	s_barrier
	ds_read_b128 v[74:77], v155
	ds_read_b128 v[78:81], v155 offset:1024
	ds_read_b128 v[82:85], v155 offset:2048
	ds_read_b128 v[110:113], v155 offset:3072
	s_add_u32 s26, s0, 0x80100
	s_addc_u32 s27, s1, 0
	s_mov_b32 m0, s14
	v_lshl_add_u64 v[150:151], s[26:27], 0, v[170:171]
	ds_read_b128 v[114:117], v153 offset:32768
	ds_read_b128 v[122:125], v153 offset:33792
	ds_read_b128 v[126:129], v153 offset:34816
	ds_read_b128 v[130:133], v153 offset:35840
	ds_read_b128 v[134:137], v153 offset:36864
	ds_read_b128 v[138:141], v153 offset:37888
	ds_read_b128 v[142:145], v153 offset:38912
	ds_read_b128 v[146:149], v153 offset:39936
	global_load_lds_dwordx4 v[150:151], off
	v_lshl_add_u64 v[150:151], s[26:27], 0, v[172:173]
	s_mov_b32 m0, s15
	s_nop 0
	global_load_lds_dwordx4 v[150:151], off
	s_waitcnt lgkmcnt(8)
	s_barrier
	s_waitcnt lgkmcnt(0)
	v_mfma_f32_16x16x32_bf16 v[86:89], v[74:77], v[114:117], v[86:89]
	v_mfma_f32_16x16x32_bf16 v[90:93], v[82:85], v[114:117], v[90:93]
	v_mfma_f32_16x16x32_bf16 v[94:97], v[74:77], v[126:129], v[94:97]
	v_mfma_f32_16x16x32_bf16 v[98:101], v[82:85], v[126:129], v[98:101]
	v_mfma_f32_16x16x32_bf16 v[102:105], v[74:77], v[134:137], v[102:105]
	v_mfma_f32_16x16x32_bf16 v[106:109], v[82:85], v[134:137], v[106:109]
	v_mfma_f32_16x16x32_bf16 v[38:41], v[74:77], v[142:145], v[38:41]
	v_mfma_f32_16x16x32_bf16 v[42:45], v[82:85], v[142:145], v[42:45]
	v_mfma_f32_16x16x32_bf16 v[86:89], v[78:81], v[122:125], v[86:89]
	v_mfma_f32_16x16x32_bf16 v[90:93], v[110:113], v[122:125], v[90:93]
	v_mfma_f32_16x16x32_bf16 v[94:97], v[78:81], v[130:133], v[94:97]
	v_mfma_f32_16x16x32_bf16 v[98:101], v[110:113], v[130:133], v[98:101]
	v_mfma_f32_16x16x32_bf16 v[102:105], v[78:81], v[138:141], v[102:105]
	v_mfma_f32_16x16x32_bf16 v[106:109], v[110:113], v[138:141], v[106:109]
	v_mfma_f32_16x16x32_bf16 v[38:41], v[78:81], v[146:149], v[38:41]
	v_mfma_f32_16x16x32_bf16 v[42:45], v[110:113], v[146:149], v[42:45]
	s_barrier
	s_mov_b64 s[26:27], 0x180
	s_mov_b32 m0, s16
	v_lshl_add_u64 v[150:151], v[34:35], 0, s[26:27]
	ds_read_b128 v[74:77], v1
	ds_read_b128 v[78:81], v1 offset:1024
	ds_read_b128 v[82:85], v1 offset:2048
	ds_read_b128 v[110:113], v1 offset:3072
	global_load_lds_dwordx4 v[150:151], off
	v_lshl_add_u64 v[150:151], v[36:37], 0, s[26:27]
	s_mov_b32 m0, s17
	s_nop 0
	global_load_lds_dwordx4 v[150:151], off
	s_barrier
	s_waitcnt lgkmcnt(0)
	v_mfma_f32_16x16x32_bf16 v[118:121], v[74:77], v[114:117], v[118:121]
	v_mfma_f32_16x16x32_bf16 v[54:57], v[82:85], v[114:117], v[54:57]
	v_mfma_f32_16x16x32_bf16 v[58:61], v[74:77], v[126:129], v[58:61]
	v_mfma_f32_16x16x32_bf16 v[62:65], v[82:85], v[126:129], v[62:65]
	v_mfma_f32_16x16x32_bf16 v[66:69], v[74:77], v[134:137], v[66:69]
	v_mfma_f32_16x16x32_bf16 v[70:73], v[82:85], v[134:137], v[70:73]
	v_mfma_f32_16x16x32_bf16 v[46:49], v[74:77], v[142:145], v[46:49]
	v_mfma_f32_16x16x32_bf16 v[50:53], v[82:85], v[142:145], v[50:53]
	v_mfma_f32_16x16x32_bf16 v[118:121], v[78:81], v[122:125], v[118:121]
	v_mfma_f32_16x16x32_bf16 v[54:57], v[110:113], v[122:125], v[54:57]
	v_mfma_f32_16x16x32_bf16 v[58:61], v[78:81], v[130:133], v[58:61]
	v_mfma_f32_16x16x32_bf16 v[62:65], v[110:113], v[130:133], v[62:65]
	v_mfma_f32_16x16x32_bf16 v[66:69], v[78:81], v[138:141], v[66:69]
	v_mfma_f32_16x16x32_bf16 v[70:73], v[110:113], v[138:141], v[70:73]
	v_mfma_f32_16x16x32_bf16 v[46:49], v[78:81], v[146:149], v[46:49]
	v_mfma_f32_16x16x32_bf16 v[50:53], v[110:113], v[146:149], v[50:53]
	s_mov_b32 m0, s10
	v_lshl_add_u64 v[74:75], v[32:33], 0, s[26:27]
	s_barrier
	global_load_lds_dwordx4 v[74:75], off
	v_lshl_add_u64 v[74:75], v[30:31], 0, s[26:27]
	s_mov_b32 m0, s11
	s_nop 0
	global_load_lds_dwordx4 v[74:75], off
	s_barrier
	s_waitcnt lgkmcnt(0)
	s_barrier
	s_add_u32 s4, s4, 0x80180
	s_addc_u32 s5, s5, 0
	s_mov_b32 m0, s12
	v_lshl_add_u64 v[74:75], s[4:5], 0, v[170:171]
	global_load_lds_dwordx4 v[74:75], off
	v_lshl_add_u64 v[74:75], s[4:5], 0, v[172:173]
	s_mov_b32 m0, s13
	s_nop 0
	global_load_lds_dwordx4 v[74:75], off
	s_waitcnt vmcnt(6)
	s_barrier
	s_barrier
	ds_read_b128 v[74:77], v152
	ds_read_b128 v[78:81], v152 offset:1024
	ds_read_b128 v[82:85], v152 offset:2048
	ds_read_b128 v[110:113], v152 offset:3072
	s_add_u32 s0, s0, 0x80180
	s_addc_u32 s1, s1, 0
	s_mov_b32 m0, s23
	v_lshl_add_u64 v[150:151], s[0:1], 0, v[170:171]
	ds_read_b128 v[114:117], v153
	ds_read_b128 v[122:125], v153 offset:1024
	ds_read_b128 v[126:129], v153 offset:2048
	ds_read_b128 v[130:133], v153 offset:3072
	ds_read_b128 v[134:137], v153 offset:4096
	ds_read_b128 v[138:141], v153 offset:5120
	ds_read_b128 v[142:145], v153 offset:6144
	ds_read_b128 v[146:149], v153 offset:7168
	global_load_lds_dwordx4 v[150:151], off
	v_lshl_add_u64 v[150:151], s[0:1], 0, v[172:173]
	s_mov_b32 m0, s20
	s_nop 0
	global_load_lds_dwordx4 v[150:151], off
	s_waitcnt lgkmcnt(8)
	s_barrier
	s_waitcnt lgkmcnt(0)
	v_mfma_f32_16x16x32_bf16 v[86:89], v[74:77], v[114:117], v[86:89]
	v_mfma_f32_16x16x32_bf16 v[90:93], v[82:85], v[114:117], v[90:93]
	v_mfma_f32_16x16x32_bf16 v[94:97], v[74:77], v[126:129], v[94:97]
	v_mfma_f32_16x16x32_bf16 v[98:101], v[82:85], v[126:129], v[98:101]
	v_mfma_f32_16x16x32_bf16 v[102:105], v[74:77], v[134:137], v[102:105]
	v_mfma_f32_16x16x32_bf16 v[106:109], v[82:85], v[134:137], v[106:109]
	v_mfma_f32_16x16x32_bf16 v[38:41], v[74:77], v[142:145], v[38:41]
	v_mfma_f32_16x16x32_bf16 v[42:45], v[82:85], v[142:145], v[42:45]
	v_mfma_f32_16x16x32_bf16 v[86:89], v[78:81], v[122:125], v[86:89]
	v_mfma_f32_16x16x32_bf16 v[90:93], v[110:113], v[122:125], v[90:93]
	v_mfma_f32_16x16x32_bf16 v[94:97], v[78:81], v[130:133], v[94:97]
	v_mfma_f32_16x16x32_bf16 v[98:101], v[110:113], v[130:133], v[98:101]
	v_mfma_f32_16x16x32_bf16 v[102:105], v[78:81], v[138:141], v[102:105]
	v_mfma_f32_16x16x32_bf16 v[106:109], v[110:113], v[138:141], v[106:109]
	v_mfma_f32_16x16x32_bf16 v[38:41], v[78:81], v[146:149], v[38:41]
	v_mfma_f32_16x16x32_bf16 v[42:45], v[110:113], v[146:149], v[42:45]
	s_barrier
	s_mov_b32 m0, s21
	ds_read_b128 v[74:77], v154
	ds_read_b128 v[78:81], v154 offset:1024
	ds_read_b128 v[82:85], v154 offset:2048
	ds_read_b128 v[110:113], v154 offset:3072
	global_load_lds_dwordx4 v[34:35], off
	s_mov_b32 m0, s22
	s_nop 0
	global_load_lds_dwordx4 v[36:37], off
	s_barrier
	s_waitcnt lgkmcnt(0)
	v_mfma_f32_16x16x32_bf16 v[34:37], v[74:77], v[114:117], v[118:121]
	v_mfma_f32_16x16x32_bf16 v[54:57], v[82:85], v[114:117], v[54:57]
	v_mfma_f32_16x16x32_bf16 v[58:61], v[74:77], v[126:129], v[58:61]
	v_mfma_f32_16x16x32_bf16 v[62:65], v[82:85], v[126:129], v[62:65]
	v_mfma_f32_16x16x32_bf16 v[66:69], v[74:77], v[134:137], v[66:69]
	v_mfma_f32_16x16x32_bf16 v[70:73], v[82:85], v[134:137], v[70:73]
	v_mfma_f32_16x16x32_bf16 v[46:49], v[74:77], v[142:145], v[46:49]
	v_mfma_f32_16x16x32_bf16 v[50:53], v[82:85], v[142:145], v[50:53]
	v_mfma_f32_16x16x32_bf16 v[34:37], v[78:81], v[122:125], v[34:37]
	v_mfma_f32_16x16x32_bf16 v[54:57], v[110:113], v[122:125], v[54:57]
	v_mfma_f32_16x16x32_bf16 v[58:61], v[78:81], v[130:133], v[58:61]
	v_mfma_f32_16x16x32_bf16 v[62:65], v[110:113], v[130:133], v[62:65]
	v_mfma_f32_16x16x32_bf16 v[66:69], v[78:81], v[138:141], v[66:69]
	v_mfma_f32_16x16x32_bf16 v[70:73], v[110:113], v[138:141], v[70:73]
	v_mfma_f32_16x16x32_bf16 v[46:49], v[78:81], v[146:149], v[46:49]
	v_mfma_f32_16x16x32_bf16 v[50:53], v[110:113], v[146:149], v[50:53]
	s_mov_b32 m0, s9
	s_barrier
	global_load_lds_dwordx4 v[32:33], off
	s_mov_b32 m0, s18
	s_nop 0
	global_load_lds_dwordx4 v[30:31], off
	s_barrier
	s_waitcnt lgkmcnt(0)
	s_barrier
	s_mov_b32 m0, s19
	s_nop 0
	global_load_lds_dwordx4 v[28:29], off
	s_mov_b32 m0, s24
	s_nop 0
	global_load_lds_dwordx4 v[26:27], off
	s_waitcnt vmcnt(6)
	s_barrier
	s_barrier
	ds_read_b128 v[26:29], v155
	ds_read_b128 v[30:33], v155 offset:1024
	ds_read_b128 v[74:77], v155 offset:2048
	ds_read_b128 v[78:81], v155 offset:3072
	s_mov_b32 m0, s14
	ds_read_b128 v[82:85], v153 offset:32768
	ds_read_b128 v[110:113], v153 offset:33792
	ds_read_b128 v[114:117], v153 offset:34816
	ds_read_b128 v[118:121], v153 offset:35840
	ds_read_b128 v[122:125], v153 offset:36864
	ds_read_b128 v[126:129], v153 offset:37888
	ds_read_b128 v[130:133], v153 offset:38912
	ds_read_b128 v[134:137], v153 offset:39936
	global_load_lds_dwordx4 v[22:23], off
	s_mov_b32 m0, s15
	s_nop 0
	global_load_lds_dwordx4 v[24:25], off
	s_waitcnt lgkmcnt(8)
	s_barrier
	s_waitcnt lgkmcnt(0)
	v_mfma_f32_16x16x32_bf16 v[22:25], v[26:29], v[82:85], v[86:89]
	v_mfma_f32_16x16x32_bf16 v[86:89], v[74:77], v[82:85], v[90:93]
	v_mfma_f32_16x16x32_bf16 v[90:93], v[26:29], v[114:117], v[94:97]
	v_mfma_f32_16x16x32_bf16 v[94:97], v[74:77], v[114:117], v[98:101]
	v_mfma_f32_16x16x32_bf16 v[98:101], v[26:29], v[122:125], v[102:105]
	v_mfma_f32_16x16x32_bf16 v[26:29], v[26:29], v[130:133], v[38:41]
	v_mfma_f32_16x16x32_bf16 v[22:25], v[30:33], v[110:113], v[22:25]
	v_mfma_f32_16x16x32_bf16 v[90:93], v[30:33], v[118:121], v[90:93]
	v_mfma_f32_16x16x32_bf16 v[98:101], v[30:33], v[126:129], v[98:101]
	v_mfma_f32_16x16x32_bf16 v[102:105], v[74:77], v[122:125], v[106:109]
	v_mfma_f32_16x16x32_bf16 v[26:29], v[30:33], v[134:137], v[26:29]
	v_mfma_f32_16x16x32_bf16 v[30:33], v[74:77], v[130:133], v[42:45]
	v_mfma_f32_16x16x32_bf16 v[86:89], v[78:81], v[110:113], v[86:89]
	v_mfma_f32_16x16x32_bf16 v[94:97], v[78:81], v[118:121], v[94:97]
	v_mfma_f32_16x16x32_bf16 v[102:105], v[78:81], v[126:129], v[102:105]
	v_mfma_f32_16x16x32_bf16 v[30:33], v[78:81], v[134:137], v[30:33]
	s_barrier
	s_mov_b32 m0, s16
	ds_read_b128 v[38:41], v1
	ds_read_b128 v[42:45], v1 offset:1024
	ds_read_b128 v[74:77], v1 offset:2048
	ds_read_b128 v[78:81], v1 offset:3072
	global_load_lds_dwordx4 v[18:19], off
	s_mov_b32 m0, s17
	s_nop 0
	global_load_lds_dwordx4 v[20:21], off
	s_barrier
	s_waitcnt lgkmcnt(0)
	v_mfma_f32_16x16x32_bf16 v[18:21], v[38:41], v[82:85], v[34:37]
	v_mfma_f32_16x16x32_bf16 v[34:37], v[74:77], v[82:85], v[54:57]
	v_mfma_f32_16x16x32_bf16 v[54:57], v[38:41], v[114:117], v[58:61]
	v_mfma_f32_16x16x32_bf16 v[58:61], v[74:77], v[114:117], v[62:65]
	v_mfma_f32_16x16x32_bf16 v[62:65], v[38:41], v[122:125], v[66:69]
	v_mfma_f32_16x16x32_bf16 v[38:41], v[38:41], v[130:133], v[46:49]
	v_mfma_f32_16x16x32_bf16 v[18:21], v[42:45], v[110:113], v[18:21]
	v_mfma_f32_16x16x32_bf16 v[54:57], v[42:45], v[118:121], v[54:57]
	v_mfma_f32_16x16x32_bf16 v[62:65], v[42:45], v[126:129], v[62:65]
	v_mfma_f32_16x16x32_bf16 v[66:69], v[74:77], v[122:125], v[70:73]
	v_mfma_f32_16x16x32_bf16 v[38:41], v[42:45], v[134:137], v[38:41]
	v_mfma_f32_16x16x32_bf16 v[42:45], v[74:77], v[130:133], v[50:53]
	v_mfma_f32_16x16x32_bf16 v[34:37], v[78:81], v[110:113], v[34:37]
	v_mfma_f32_16x16x32_bf16 v[58:61], v[78:81], v[118:121], v[58:61]
	v_mfma_f32_16x16x32_bf16 v[66:69], v[78:81], v[126:129], v[66:69]
	v_mfma_f32_16x16x32_bf16 v[42:45], v[78:81], v[134:137], v[42:45]
	s_mov_b32 m0, s10
	s_barrier
	global_load_lds_dwordx4 v[2:3], off
	s_mov_b32 m0, s11
	s_nop 0
	global_load_lds_dwordx4 v[6:7], off
	s_barrier
	s_waitcnt lgkmcnt(0)
	s_barrier
	s_mov_b32 m0, s12
	s_nop 0
	global_load_lds_dwordx4 v[10:11], off
	s_mov_b32 m0, s13
	s_nop 0
	global_load_lds_dwordx4 v[12:13], off
	s_waitcnt vmcnt(6)
	s_barrier
	s_lshl_b32 s0, s7, 8
	v_lshl_or_b32 v1, v211, 2, s0
	s_ashr_i32 s0, s82, 2
	s_ashr_i32 s1, s0, 31
	s_lshl_b64 s[0:1], s[0:1], 19
	v_or_b32_e32 v1, s8, v1
	s_add_u32 s0, s94, s0
	s_addc_u32 s1, s95, s1
	v_lshlrev_b32_e32 v170, 2, v1
	v_lshl_add_u64 v[2:3], s[0:1], 0, v[170:171]
	s_mov_b64 s[0:1], 0xb3d6400
	v_lshl_add_u64 v[2:3], v[2:3], 0, s[0:1]
	v_lshl_add_u64 v[6:7], v[2:3], 0, v[8:9]
	v_lshl_add_u64 v[4:5], v[2:3], 0, v[4:5]
	s_barrier
	global_store_dwordx4 v[6:7], v[22:25], off
	global_store_dwordx4 v[6:7], v[86:89], off offset:64
	global_store_dwordx4 v[6:7], v[18:21], off offset:512
	global_store_dwordx4 v[6:7], v[34:37], off offset:576
	global_store_dwordx4 v[4:5], v[90:93], off
	global_store_dwordx4 v[4:5], v[94:97], off offset:64
	global_store_dwordx4 v[4:5], v[54:57], off offset:512
	global_store_dwordx4 v[4:5], v[58:61], off offset:576
	v_lshl_add_u64 v[4:5], v[2:3], 0, v[16:17]
	v_lshl_add_u64 v[2:3], v[2:3], 0, v[14:15]
	global_store_dwordx4 v[4:5], v[98:101], off
	global_store_dwordx4 v[4:5], v[102:105], off offset:64
	global_store_dwordx4 v[4:5], v[62:65], off offset:512
	global_store_dwordx4 v[4:5], v[66:69], off offset:576
	global_store_dwordx4 v[2:3], v[26:29], off
	global_store_dwordx4 v[2:3], v[30:33], off offset:64
	global_store_dwordx4 v[2:3], v[38:41], off offset:512
	global_store_dwordx4 v[2:3], v[42:45], off offset:576
	s_waitcnt vmcnt(0)
	s_cmpk_gt_u32 s6, 0xff
	s_cbranch_scc1 .LBB0_950
	s_barrier

.LBB0_1205:
	s_add_i32 s24, 0, 0x18000
	s_lshl_b32 s8, s8, 5
	s_add_i32 s16, s24, s19
	s_mov_b64 s[12:13], 0x80
	s_lshl_b32 s21, s20, 13
	s_and_b32 s8, s8, 0x60
	v_lshl_add_u64 v[18:19], v[34:35], 0, s[12:13]
	s_mov_b32 m0, s16
	s_add_i32 s17, s16, 0x2000
	s_add_i32 s10, s9, 0x8000
	s_add_i32 s11, s9, 0xa000
	s_waitcnt vmcnt(4)
	s_barrier
	global_load_lds_dwordx4 v[18:19], off
	v_lshl_add_u64 v[20:21], v[36:37], 0, s[12:13]
	s_mov_b32 m0, s17
	s_add_u32 s22, s2, 0xb0080
	global_load_lds_dwordx4 v[20:21], off
	v_lshl_add_u64 v[2:3], v[32:33], 0, s[12:13]
	s_mov_b32 m0, s10
	s_addc_u32 s23, s3, 0
	s_add_i32 s25, 0, 0x1c000
	global_load_lds_dwordx4 v[2:3], off
	v_lshl_add_u64 v[6:7], v[30:31], 0, s[12:13]
	s_mov_b32 m0, s11
	s_add_i32 s12, s25, s19
	global_load_lds_dwordx4 v[6:7], off
	v_lshl_add_u64 v[10:11], s[22:23], 0, v[130:131]
	s_mov_b32 m0, s12
	s_add_i32 s13, s12, 0x2000
	global_load_lds_dwordx4 v[10:11], off
	v_lshl_add_u64 v[12:13], s[22:23], 0, v[132:133]
	s_mov_b32 m0, s13
	v_lshl_or_b32 v1, s8, 7, v1
	global_load_lds_dwordx4 v[12:13], off
	s_add_i32 s22, 0, 0x10000
	v_add_u32_e32 v156, s22, v1
	s_waitcnt vmcnt(6)
	s_barrier
	ds_read_b128 v[38:41], v156
	ds_read_b128 v[42:45], v156 offset:1024
	ds_read_b128 v[46:49], v156 offset:2048
	ds_read_b128 v[50:53], v156 offset:3072
	v_lshlrev_b32_e32 v5, 2, v178
	v_lshl_or_b32 v4, v178, 6, v204
	v_and_b32_e32 v5, 32, v5
	v_lshl_or_b32 v14, s20, 6, v178
	v_bitop3_b32 v4, v4, s21, v5 bitop3:0xde
	v_mov_b32_e32 v15, v131
	v_add_u32_e32 v157, 0, v4
	s_add_i32 s26, 0, 0x14000
	v_lshlrev_b64 v[8:9], 12, v[14:15]
	v_or_b32_e32 v4, 16, v14
	v_mov_b32_e32 v5, v131
	v_or_b32_e32 v16, 32, v14
	v_mov_b32_e32 v17, v131
	v_or_b32_e32 v14, 48, v14
	v_add_u32_e32 v158, s26, v1
	v_add_u32_e32 v159, s24, v1
	v_add_u32_e32 v1, s25, v1
	v_lshlrev_b64 v[4:5], 12, v[4:5]
	v_lshlrev_b64 v[16:17], 12, v[16:17]
	v_lshlrev_b64 v[14:15], 12, v[14:15]
	s_add_u32 s20, s0, 0xb0080
	s_addc_u32 s21, s1, 0
	s_add_i32 s23, s9, 0xc000
	v_lshl_add_u64 v[86:87], s[20:21], 0, v[130:131]
	s_mov_b32 m0, s23
	ds_read_b128 v[54:57], v157
	ds_read_b128 v[58:61], v157 offset:1024
	ds_read_b128 v[62:65], v157 offset:2048
	ds_read_b128 v[66:69], v157 offset:3072
	ds_read_b128 v[70:73], v157 offset:4096
	ds_read_b128 v[74:77], v157 offset:5120
	ds_read_b128 v[78:81], v157 offset:6144
	ds_read_b128 v[82:85], v157 offset:7168
	global_load_lds_dwordx4 v[86:87], off
	v_lshl_add_u64 v[86:87], s[20:21], 0, v[132:133]
	s_add_i32 s20, s9, 0xe000
	s_mov_b32 m0, s20
	s_nop 0
	global_load_lds_dwordx4 v[86:87], off
	s_waitcnt lgkmcnt(8)
	s_barrier
	s_waitcnt lgkmcnt(0)
	v_mfma_f32_16x16x32_bf16 v[86:89], v[38:41], v[54:57], 0
	v_mfma_f32_16x16x32_bf16 v[94:97], v[38:41], v[62:65], 0
	v_mfma_f32_16x16x32_bf16 v[102:105], v[38:41], v[70:73], 0
	v_mfma_f32_16x16x32_bf16 v[38:41], v[38:41], v[78:81], 0
	v_mfma_f32_16x16x32_bf16 v[86:89], v[42:45], v[58:61], v[86:89]
	v_mfma_f32_16x16x32_bf16 v[90:93], v[46:49], v[54:57], 0
	v_mfma_f32_16x16x32_bf16 v[94:97], v[42:45], v[66:69], v[94:97]
	v_mfma_f32_16x16x32_bf16 v[98:101], v[46:49], v[62:65], 0
	v_mfma_f32_16x16x32_bf16 v[102:105], v[42:45], v[74:77], v[102:105]
	v_mfma_f32_16x16x32_bf16 v[106:109], v[46:49], v[70:73], 0
	v_mfma_f32_16x16x32_bf16 v[38:41], v[42:45], v[82:85], v[38:41]
	v_mfma_f32_16x16x32_bf16 v[42:45], v[46:49], v[78:81], 0
	v_mfma_f32_16x16x32_bf16 v[90:93], v[50:53], v[58:61], v[90:93]
	v_mfma_f32_16x16x32_bf16 v[98:101], v[50:53], v[66:69], v[98:101]
	v_mfma_f32_16x16x32_bf16 v[106:109], v[50:53], v[74:77], v[106:109]
	v_mfma_f32_16x16x32_bf16 v[42:45], v[50:53], v[82:85], v[42:45]
	s_barrier
	s_mov_b64 s[24:25], 0x100
	s_add_i32 s21, s22, s19
	v_lshl_add_u64 v[118:119], v[34:35], 0, s[24:25]
	s_mov_b32 m0, s21
	s_add_i32 s22, s21, 0x2000
	ds_read_b128 v[46:49], v158
	ds_read_b128 v[50:53], v158 offset:1024
	ds_read_b128 v[110:113], v158 offset:2048
	ds_read_b128 v[114:117], v158 offset:3072
	global_load_lds_dwordx4 v[118:119], off
	v_lshl_add_u64 v[118:119], v[36:37], 0, s[24:25]
	s_mov_b32 m0, s22
	s_nop 0
	global_load_lds_dwordx4 v[118:119], off
	s_barrier
	s_waitcnt lgkmcnt(0)
	v_mfma_f32_16x16x32_bf16 v[118:121], v[46:49], v[54:57], 0
	v_mfma_f32_16x16x32_bf16 v[54:57], v[110:113], v[54:57], 0
	v_mfma_f32_16x16x32_bf16 v[118:121], v[50:53], v[58:61], v[118:121]
	v_mfma_f32_16x16x32_bf16 v[54:57], v[114:117], v[58:61], v[54:57]
	v_mfma_f32_16x16x32_bf16 v[58:61], v[46:49], v[62:65], 0
	v_mfma_f32_16x16x32_bf16 v[62:65], v[110:113], v[62:65], 0
	v_mfma_f32_16x16x32_bf16 v[58:61], v[50:53], v[66:69], v[58:61]
	v_mfma_f32_16x16x32_bf16 v[62:65], v[114:117], v[66:69], v[62:65]
	v_mfma_f32_16x16x32_bf16 v[66:69], v[46:49], v[70:73], 0
	v_mfma_f32_16x16x32_bf16 v[46:49], v[46:49], v[78:81], 0
	v_mfma_f32_16x16x32_bf16 v[66:69], v[50:53], v[74:77], v[66:69]
	v_mfma_f32_16x16x32_bf16 v[70:73], v[110:113], v[70:73], 0
	v_mfma_f32_16x16x32_bf16 v[46:49], v[50:53], v[82:85], v[46:49]
	v_mfma_f32_16x16x32_bf16 v[50:53], v[110:113], v[78:81], 0
	v_mfma_f32_16x16x32_bf16 v[70:73], v[114:117], v[74:77], v[70:73]
	v_mfma_f32_16x16x32_bf16 v[50:53], v[114:117], v[82:85], v[50:53]
	s_mov_b32 m0, s9
	v_lshl_add_u64 v[74:75], v[32:33], 0, s[24:25]
	s_barrier
	global_load_lds_dwordx4 v[74:75], off
	v_lshl_add_u64 v[74:75], v[30:31], 0, s[24:25]
	s_mov_b32 m0, s18
	s_nop 0
	global_load_lds_dwordx4 v[74:75], off
	s_barrier
	s_waitcnt lgkmcnt(0)
	s_barrier
	s_add_u32 s24, s2, 0xb0100
	s_addc_u32 s25, s3, 0
	s_add_i32 s19, s26, s19
	v_lshl_add_u64 v[74:75], s[24:25], 0, v[130:131]
	s_mov_b32 m0, s19
	s_nop 0
	global_load_lds_dwordx4 v[74:75], off
	v_lshl_add_u64 v[74:75], s[24:25], 0, v[132:133]
	s_add_i32 s24, s19, 0x2000
	s_mov_b32 m0, s24
	s_nop 0
	global_load_lds_dwordx4 v[74:75], off
	s_waitcnt vmcnt(6)
	s_barrier
	s_barrier
	ds_read_b128 v[74:77], v159
	ds_read_b128 v[78:81], v159 offset:1024
	ds_read_b128 v[82:85], v159 offset:2048
	ds_read_b128 v[110:113], v159 offset:3072
	s_add_u32 s26, s0, 0xb0100
	s_addc_u32 s27, s1, 0
	s_mov_b32 m0, s14
	v_lshl_add_u64 v[154:155], s[26:27], 0, v[130:131]
	ds_read_b128 v[114:117], v157 offset:32768
	ds_read_b128 v[122:125], v157 offset:33792
	ds_read_b128 v[126:129], v157 offset:34816
	ds_read_b128 v[134:137], v157 offset:35840
	ds_read_b128 v[138:141], v157 offset:36864
	ds_read_b128 v[142:145], v157 offset:37888
	ds_read_b128 v[146:149], v157 offset:38912
	ds_read_b128 v[150:153], v157 offset:39936
	global_load_lds_dwordx4 v[154:155], off
	v_lshl_add_u64 v[154:155], s[26:27], 0, v[132:133]
	s_mov_b32 m0, s15
	s_nop 0
	global_load_lds_dwordx4 v[154:155], off
	s_waitcnt lgkmcnt(8)
	s_barrier
	s_waitcnt lgkmcnt(0)
	v_mfma_f32_16x16x32_bf16 v[86:89], v[74:77], v[114:117], v[86:89]
	v_mfma_f32_16x16x32_bf16 v[90:93], v[82:85], v[114:117], v[90:93]
	v_mfma_f32_16x16x32_bf16 v[94:97], v[74:77], v[126:129], v[94:97]
	v_mfma_f32_16x16x32_bf16 v[98:101], v[82:85], v[126:129], v[98:101]
	v_mfma_f32_16x16x32_bf16 v[102:105], v[74:77], v[138:141], v[102:105]
	v_mfma_f32_16x16x32_bf16 v[106:109], v[82:85], v[138:141], v[106:109]
	v_mfma_f32_16x16x32_bf16 v[38:41], v[74:77], v[146:149], v[38:41]
	v_mfma_f32_16x16x32_bf16 v[42:45], v[82:85], v[146:149], v[42:45]
	v_mfma_f32_16x16x32_bf16 v[86:89], v[78:81], v[122:125], v[86:89]
	v_mfma_f32_16x16x32_bf16 v[90:93], v[110:113], v[122:125], v[90:93]
	v_mfma_f32_16x16x32_bf16 v[94:97], v[78:81], v[134:137], v[94:97]
	v_mfma_f32_16x16x32_bf16 v[98:101], v[110:113], v[134:137], v[98:101]
	v_mfma_f32_16x16x32_bf16 v[102:105], v[78:81], v[142:145], v[102:105]
	v_mfma_f32_16x16x32_bf16 v[106:109], v[110:113], v[142:145], v[106:109]
	v_mfma_f32_16x16x32_bf16 v[38:41], v[78:81], v[150:153], v[38:41]
	v_mfma_f32_16x16x32_bf16 v[42:45], v[110:113], v[150:153], v[42:45]
	s_barrier
	s_mov_b64 s[26:27], 0x180
	s_mov_b32 m0, s16
	v_lshl_add_u64 v[154:155], v[34:35], 0, s[26:27]
	ds_read_b128 v[74:77], v1
	ds_read_b128 v[78:81], v1 offset:1024
	ds_read_b128 v[82:85], v1 offset:2048
	ds_read_b128 v[110:113], v1 offset:3072
	global_load_lds_dwordx4 v[154:155], off
	v_lshl_add_u64 v[154:155], v[36:37], 0, s[26:27]
	s_mov_b32 m0, s17
	s_nop 0
	global_load_lds_dwordx4 v[154:155], off
	s_barrier
	s_waitcnt lgkmcnt(0)
	v_mfma_f32_16x16x32_bf16 v[118:121], v[74:77], v[114:117], v[118:121]
	v_mfma_f32_16x16x32_bf16 v[54:57], v[82:85], v[114:117], v[54:57]
	v_mfma_f32_16x16x32_bf16 v[58:61], v[74:77], v[126:129], v[58:61]
	v_mfma_f32_16x16x32_bf16 v[62:65], v[82:85], v[126:129], v[62:65]
	v_mfma_f32_16x16x32_bf16 v[66:69], v[74:77], v[138:141], v[66:69]
	v_mfma_f32_16x16x32_bf16 v[70:73], v[82:85], v[138:141], v[70:73]
	v_mfma_f32_16x16x32_bf16 v[46:49], v[74:77], v[146:149], v[46:49]
	v_mfma_f32_16x16x32_bf16 v[50:53], v[82:85], v[146:149], v[50:53]
	v_mfma_f32_16x16x32_bf16 v[118:121], v[78:81], v[122:125], v[118:121]
	v_mfma_f32_16x16x32_bf16 v[54:57], v[110:113], v[122:125], v[54:57]
	v_mfma_f32_16x16x32_bf16 v[58:61], v[78:81], v[134:137], v[58:61]
	v_mfma_f32_16x16x32_bf16 v[62:65], v[110:113], v[134:137], v[62:65]
	v_mfma_f32_16x16x32_bf16 v[66:69], v[78:81], v[142:145], v[66:69]
	v_mfma_f32_16x16x32_bf16 v[70:73], v[110:113], v[142:145], v[70:73]
	v_mfma_f32_16x16x32_bf16 v[46:49], v[78:81], v[150:153], v[46:49]
	v_mfma_f32_16x16x32_bf16 v[50:53], v[110:113], v[150:153], v[50:53]
	s_mov_b32 m0, s10
	v_lshl_add_u64 v[74:75], v[32:33], 0, s[26:27]
	s_barrier
	global_load_lds_dwordx4 v[74:75], off
	v_lshl_add_u64 v[74:75], v[30:31], 0, s[26:27]
	s_mov_b32 m0, s11
	s_nop 0
	global_load_lds_dwordx4 v[74:75], off
	s_barrier
	s_waitcnt lgkmcnt(0)
	s_barrier
	s_add_u32 s2, s2, 0xb0180
	s_addc_u32 s3, s3, 0
	s_mov_b32 m0, s12
	v_lshl_add_u64 v[74:75], s[2:3], 0, v[130:131]
	global_load_lds_dwordx4 v[74:75], off
	v_lshl_add_u64 v[74:75], s[2:3], 0, v[132:133]
	s_mov_b32 m0, s13
	s_nop 0
	global_load_lds_dwordx4 v[74:75], off
	s_waitcnt vmcnt(6)
	s_barrier
	s_barrier
	ds_read_b128 v[74:77], v156
	ds_read_b128 v[78:81], v156 offset:1024
	ds_read_b128 v[82:85], v156 offset:2048
	ds_read_b128 v[110:113], v156 offset:3072
	s_add_u32 s0, s0, 0xb0180
	s_addc_u32 s1, s1, 0
	s_mov_b32 m0, s23
	v_lshl_add_u64 v[154:155], s[0:1], 0, v[130:131]
	ds_read_b128 v[114:117], v157
	ds_read_b128 v[122:125], v157 offset:1024
	ds_read_b128 v[126:129], v157 offset:2048
	ds_read_b128 v[134:137], v157 offset:3072
	ds_read_b128 v[138:141], v157 offset:4096
	ds_read_b128 v[142:145], v157 offset:5120
	ds_read_b128 v[146:149], v157 offset:6144
	ds_read_b128 v[150:153], v157 offset:7168
	global_load_lds_dwordx4 v[154:155], off
	v_lshl_add_u64 v[132:133], s[0:1], 0, v[132:133]
	s_mov_b32 m0, s20
	s_nop 0
	global_load_lds_dwordx4 v[132:133], off
	s_waitcnt lgkmcnt(8)
	s_barrier
	s_waitcnt lgkmcnt(0)
	v_mfma_f32_16x16x32_bf16 v[86:89], v[74:77], v[114:117], v[86:89]
	v_mfma_f32_16x16x32_bf16 v[90:93], v[82:85], v[114:117], v[90:93]
	v_mfma_f32_16x16x32_bf16 v[94:97], v[74:77], v[126:129], v[94:97]
	v_mfma_f32_16x16x32_bf16 v[98:101], v[82:85], v[126:129], v[98:101]
	v_mfma_f32_16x16x32_bf16 v[102:105], v[74:77], v[138:141], v[102:105]
	v_mfma_f32_16x16x32_bf16 v[106:109], v[82:85], v[138:141], v[106:109]
	v_mfma_f32_16x16x32_bf16 v[38:41], v[74:77], v[146:149], v[38:41]
	v_mfma_f32_16x16x32_bf16 v[42:45], v[82:85], v[146:149], v[42:45]
	v_mfma_f32_16x16x32_bf16 v[86:89], v[78:81], v[122:125], v[86:89]
	v_mfma_f32_16x16x32_bf16 v[90:93], v[110:113], v[122:125], v[90:93]
	v_mfma_f32_16x16x32_bf16 v[94:97], v[78:81], v[134:137], v[94:97]
	v_mfma_f32_16x16x32_bf16 v[98:101], v[110:113], v[134:137], v[98:101]
	v_mfma_f32_16x16x32_bf16 v[102:105], v[78:81], v[142:145], v[102:105]
	v_mfma_f32_16x16x32_bf16 v[106:109], v[110:113], v[142:145], v[106:109]
	v_mfma_f32_16x16x32_bf16 v[38:41], v[78:81], v[150:153], v[38:41]
	v_mfma_f32_16x16x32_bf16 v[42:45], v[110:113], v[150:153], v[42:45]
	s_barrier
	s_mov_b32 m0, s21
	ds_read_b128 v[74:77], v158
	ds_read_b128 v[78:81], v158 offset:1024
	ds_read_b128 v[82:85], v158 offset:2048
	ds_read_b128 v[110:113], v158 offset:3072
	global_load_lds_dwordx4 v[34:35], off
	s_mov_b32 m0, s22
	s_nop 0
	global_load_lds_dwordx4 v[36:37], off
	s_barrier
	s_waitcnt lgkmcnt(0)
	v_mfma_f32_16x16x32_bf16 v[34:37], v[74:77], v[114:117], v[118:121]
	v_mfma_f32_16x16x32_bf16 v[54:57], v[82:85], v[114:117], v[54:57]
	v_mfma_f32_16x16x32_bf16 v[58:61], v[74:77], v[126:129], v[58:61]
	v_mfma_f32_16x16x32_bf16 v[62:65], v[82:85], v[126:129], v[62:65]
	v_mfma_f32_16x16x32_bf16 v[66:69], v[74:77], v[138:141], v[66:69]
	v_mfma_f32_16x16x32_bf16 v[70:73], v[82:85], v[138:141], v[70:73]
	v_mfma_f32_16x16x32_bf16 v[46:49], v[74:77], v[146:149], v[46:49]
	v_mfma_f32_16x16x32_bf16 v[50:53], v[82:85], v[146:149], v[50:53]
	v_mfma_f32_16x16x32_bf16 v[34:37], v[78:81], v[122:125], v[34:37]
	v_mfma_f32_16x16x32_bf16 v[54:57], v[110:113], v[122:125], v[54:57]
	v_mfma_f32_16x16x32_bf16 v[58:61], v[78:81], v[134:137], v[58:61]
	v_mfma_f32_16x16x32_bf16 v[62:65], v[110:113], v[134:137], v[62:65]
	v_mfma_f32_16x16x32_bf16 v[66:69], v[78:81], v[142:145], v[66:69]
	v_mfma_f32_16x16x32_bf16 v[70:73], v[110:113], v[142:145], v[70:73]
	v_mfma_f32_16x16x32_bf16 v[46:49], v[78:81], v[150:153], v[46:49]
	v_mfma_f32_16x16x32_bf16 v[50:53], v[110:113], v[150:153], v[50:53]
	s_mov_b32 m0, s9
	s_barrier
	global_load_lds_dwordx4 v[32:33], off
	s_mov_b32 m0, s18
	s_nop 0
	global_load_lds_dwordx4 v[30:31], off
	s_barrier
	s_waitcnt lgkmcnt(0)
	s_barrier
	s_mov_b32 m0, s19
	s_nop 0
	global_load_lds_dwordx4 v[28:29], off
	s_mov_b32 m0, s24
	s_nop 0
	global_load_lds_dwordx4 v[26:27], off
	s_waitcnt vmcnt(6)
	s_barrier
	s_barrier
	ds_read_b128 v[26:29], v159
	ds_read_b128 v[30:33], v159 offset:1024
	ds_read_b128 v[74:77], v159 offset:2048
	ds_read_b128 v[78:81], v159 offset:3072
	s_mov_b32 m0, s14
	ds_read_b128 v[82:85], v157 offset:32768
	ds_read_b128 v[110:113], v157 offset:33792
	ds_read_b128 v[114:117], v157 offset:34816
	ds_read_b128 v[118:121], v157 offset:35840
	ds_read_b128 v[122:125], v157 offset:36864
	ds_read_b128 v[126:129], v157 offset:37888
	ds_read_b128 v[132:135], v157 offset:38912
	ds_read_b128 v[136:139], v157 offset:39936
	global_load_lds_dwordx4 v[22:23], off
	s_mov_b32 m0, s15
	s_nop 0
	global_load_lds_dwordx4 v[24:25], off
	s_waitcnt lgkmcnt(8)
	s_barrier
	s_waitcnt lgkmcnt(0)
	v_mfma_f32_16x16x32_bf16 v[22:25], v[26:29], v[82:85], v[86:89]
	v_mfma_f32_16x16x32_bf16 v[86:89], v[74:77], v[82:85], v[90:93]
	v_mfma_f32_16x16x32_bf16 v[90:93], v[26:29], v[114:117], v[94:97]
	v_mfma_f32_16x16x32_bf16 v[94:97], v[74:77], v[114:117], v[98:101]
	v_mfma_f32_16x16x32_bf16 v[98:101], v[26:29], v[122:125], v[102:105]
	v_mfma_f32_16x16x32_bf16 v[26:29], v[26:29], v[132:135], v[38:41]
	v_mfma_f32_16x16x32_bf16 v[22:25], v[30:33], v[110:113], v[22:25]
	v_mfma_f32_16x16x32_bf16 v[90:93], v[30:33], v[118:121], v[90:93]
	v_mfma_f32_16x16x32_bf16 v[98:101], v[30:33], v[126:129], v[98:101]
	v_mfma_f32_16x16x32_bf16 v[102:105], v[74:77], v[122:125], v[106:109]
	v_mfma_f32_16x16x32_bf16 v[26:29], v[30:33], v[136:139], v[26:29]
	v_mfma_f32_16x16x32_bf16 v[30:33], v[74:77], v[132:135], v[42:45]
	v_mfma_f32_16x16x32_bf16 v[86:89], v[78:81], v[110:113], v[86:89]
	v_mfma_f32_16x16x32_bf16 v[94:97], v[78:81], v[118:121], v[94:97]
	v_mfma_f32_16x16x32_bf16 v[102:105], v[78:81], v[126:129], v[102:105]
	v_mfma_f32_16x16x32_bf16 v[30:33], v[78:81], v[136:139], v[30:33]
	s_barrier
	s_mov_b32 m0, s16
	ds_read_b128 v[38:41], v1
	ds_read_b128 v[42:45], v1 offset:1024
	ds_read_b128 v[74:77], v1 offset:2048
	ds_read_b128 v[78:81], v1 offset:3072
	global_load_lds_dwordx4 v[18:19], off
	s_mov_b32 m0, s17
	s_nop 0
	global_load_lds_dwordx4 v[20:21], off
	s_barrier
	s_waitcnt lgkmcnt(0)
	v_mfma_f32_16x16x32_bf16 v[18:21], v[38:41], v[82:85], v[34:37]
	v_mfma_f32_16x16x32_bf16 v[34:37], v[74:77], v[82:85], v[54:57]
	v_mfma_f32_16x16x32_bf16 v[54:57], v[38:41], v[114:117], v[58:61]
	v_mfma_f32_16x16x32_bf16 v[58:61], v[74:77], v[114:117], v[62:65]
	v_mfma_f32_16x16x32_bf16 v[62:65], v[38:41], v[122:125], v[66:69]
	v_mfma_f32_16x16x32_bf16 v[38:41], v[38:41], v[132:135], v[46:49]
	v_mfma_f32_16x16x32_bf16 v[18:21], v[42:45], v[110:113], v[18:21]
	v_mfma_f32_16x16x32_bf16 v[54:57], v[42:45], v[118:121], v[54:57]
	v_mfma_f32_16x16x32_bf16 v[62:65], v[42:45], v[126:129], v[62:65]
	v_mfma_f32_16x16x32_bf16 v[66:69], v[74:77], v[122:125], v[70:73]
	v_mfma_f32_16x16x32_bf16 v[38:41], v[42:45], v[136:139], v[38:41]
	v_mfma_f32_16x16x32_bf16 v[42:45], v[74:77], v[132:135], v[50:53]
	v_mfma_f32_16x16x32_bf16 v[34:37], v[78:81], v[110:113], v[34:37]
	v_mfma_f32_16x16x32_bf16 v[58:61], v[78:81], v[118:121], v[58:61]
	v_mfma_f32_16x16x32_bf16 v[66:69], v[78:81], v[126:129], v[66:69]
	v_mfma_f32_16x16x32_bf16 v[42:45], v[78:81], v[136:139], v[42:45]
	s_mov_b32 m0, s10
	s_barrier
	global_load_lds_dwordx4 v[2:3], off
	s_mov_b32 m0, s11
	s_nop 0
	global_load_lds_dwordx4 v[6:7], off
	s_barrier
	s_waitcnt lgkmcnt(0)
	s_barrier
	s_mov_b32 m0, s12
	s_nop 0
	global_load_lds_dwordx4 v[10:11], off
	s_mov_b32 m0, s13
	s_nop 0
	global_load_lds_dwordx4 v[12:13], off
	s_waitcnt vmcnt(6)
	s_barrier
	s_lshl_b32 s0, s5, 8
	v_lshl_or_b32 v1, v211, 2, s0
	s_ashr_i32 s0, s82, 2
	s_ashr_i32 s1, s0, 31
	s_lshl_b64 s[0:1], s[0:1], 19
	v_or_b32_e32 v1, s8, v1
	s_add_u32 s0, s94, s0
	s_addc_u32 s1, s95, s1
	v_lshlrev_b32_e32 v130, 2, v1
	v_lshl_add_u64 v[2:3], s[0:1], 0, v[130:131]
	s_mov_b64 s[0:1], 0xb3d6400
	v_lshl_add_u64 v[2:3], v[2:3], 0, s[0:1]
	v_lshl_add_u64 v[6:7], v[2:3], 0, v[8:9]
	v_lshl_add_u64 v[4:5], v[2:3], 0, v[4:5]
	s_barrier
	global_store_dwordx4 v[6:7], v[22:25], off
	global_store_dwordx4 v[6:7], v[86:89], off offset:64
	global_store_dwordx4 v[6:7], v[18:21], off offset:512
	global_store_dwordx4 v[6:7], v[34:37], off offset:576
	global_store_dwordx4 v[4:5], v[90:93], off
	global_store_dwordx4 v[4:5], v[94:97], off offset:64
	global_store_dwordx4 v[4:5], v[54:57], off offset:512
	global_store_dwordx4 v[4:5], v[58:61], off offset:576
	v_lshl_add_u64 v[4:5], v[2:3], 0, v[16:17]
	v_lshl_add_u64 v[2:3], v[2:3], 0, v[14:15]
	global_store_dwordx4 v[4:5], v[98:101], off
	global_store_dwordx4 v[4:5], v[102:105], off offset:64
	global_store_dwordx4 v[4:5], v[62:65], off offset:512
	global_store_dwordx4 v[4:5], v[66:69], off offset:576
	global_store_dwordx4 v[2:3], v[26:29], off
	global_store_dwordx4 v[2:3], v[30:33], off offset:64
	global_store_dwordx4 v[2:3], v[38:41], off offset:512
	global_store_dwordx4 v[2:3], v[42:45], off offset:576
	s_waitcnt vmcnt(0)
	s_cmpk_gt_u32 s4, 0xff
	s_cbranch_scc1 .LBB0_1207
	s_barrier
